# grid barrier between mixer and Hyena-output transpose replaced by per-channel-group completion counters (Hyena output written through, transpose spins on its group counter and reads with sc1 loads)
# speedup vs baseline: 1.0060x; 1.0060x over previous
.LBB0_965:
	s_or_b64 exec, exec, s[18:19]
	s_lshl_b64 s[18:19], s[12:13], 8
	s_ashr_i32 s13, s22, 5
	v_and_or_b32 v6, s13, -2, v26
	v_mul_lo_u32 v2, v6, s50
	v_add_u32_e32 v8, 0x100, v2
	v_or_b32_e32 v2, v8, v29
	v_lshl_add_u32 v7, v2, 1, 0
	v_add_u32_e32 v43, 0x102c0, v7
	s_waitcnt lgkmcnt(0)
	s_barrier
	ds_read_b128 v[2:5], v39 offset:960
	ds_read_b128 v[44:47], v39 offset:928
	ds_read_b128 v[48:51], v43
	v_add_u32_e32 v43, 0x10280, v7
	s_waitcnt lgkmcnt(0)
	v_mfma_f32_16x16x32_bf16 v[2:5], v[2:5], v[48:51], 0
	v_add_u32_e32 v9, 0x10100, v7
	v_lshlrev_b32_e32 v6, 8, v6
	v_mov_b32_e32 v25, v24
	v_mfma_f32_16x16x32_bf16 v[44:47], v[44:47], v[48:51], 0
	ds_read_b128 v[48:51], v39 offset:896
	ds_read_b128 v[52:55], v39 offset:864
	ds_read_b128 v[56:59], v43
	v_add_u32_e32 v43, 0x10240, v7
	s_waitcnt lgkmcnt(0)
	v_mfma_f32_16x16x32_bf16 v[2:5], v[48:51], v[56:59], v[2:5]
	s_add_i32 s12, s12, s26
	s_cmpk_lt_i32 s12, 0x100
	v_mfma_f32_16x16x32_bf16 v[44:47], v[52:55], v[56:59], v[44:47]
	ds_read_b128 v[48:51], v39 offset:832
	ds_read_b128 v[52:55], v39 offset:800
	ds_read_b128 v[56:59], v43
	v_add_u32_e32 v43, 0x10200, v7
	s_waitcnt lgkmcnt(0)
	v_mfma_f32_16x16x32_bf16 v[2:5], v[48:51], v[56:59], v[2:5]
	v_mfma_f32_16x16x32_bf16 v[44:47], v[52:55], v[56:59], v[44:47]
	ds_read_b128 v[48:51], v39 offset:768
	ds_read_b128 v[52:55], v39 offset:736
	ds_read_b128 v[56:59], v43
	v_add_u32_e32 v43, 0x101c0, v7
	s_waitcnt lgkmcnt(0)
	v_mfma_f32_16x16x32_bf16 v[2:5], v[48:51], v[56:59], v[2:5]
	v_mfma_f32_16x16x32_bf16 v[44:47], v[52:55], v[56:59], v[44:47]
	ds_read_b128 v[48:51], v39 offset:704
	ds_read_b128 v[52:55], v39 offset:672
	ds_read_b128 v[56:59], v43
	v_add_u32_e32 v43, 0x10180, v7
	s_waitcnt lgkmcnt(0)
	v_mfma_f32_16x16x32_bf16 v[2:5], v[48:51], v[56:59], v[2:5]
	v_mfma_f32_16x16x32_bf16 v[44:47], v[52:55], v[56:59], v[44:47]
	ds_read_b128 v[48:51], v39 offset:640
	ds_read_b128 v[52:55], v39 offset:608
	ds_read_b128 v[56:59], v43
	v_add_u32_e32 v43, 0x10140, v7
	s_waitcnt lgkmcnt(0)
	v_mfma_f32_16x16x32_bf16 v[2:5], v[48:51], v[56:59], v[2:5]
	v_mfma_f32_16x16x32_bf16 v[44:47], v[52:55], v[56:59], v[44:47]
	ds_read_b128 v[48:51], v39 offset:576
	ds_read_b128 v[52:55], v39 offset:544
	ds_read_b128 v[56:59], v43
	s_waitcnt lgkmcnt(0)
	v_mfma_f32_16x16x32_bf16 v[2:5], v[48:51], v[56:59], v[2:5]
	v_mfma_f32_16x16x32_bf16 v[44:47], v[52:55], v[56:59], v[44:47]
	ds_read_b128 v[48:51], v39 offset:512
	ds_read_b128 v[52:55], v39 offset:480
	ds_read_b128 v[56:59], v9
	v_add_u32_e32 v9, 0x100c0, v7
	s_waitcnt lgkmcnt(0)
	v_mfma_f32_16x16x32_bf16 v[2:5], v[48:51], v[56:59], v[2:5]
	v_mfma_f32_16x16x32_bf16 v[44:47], v[52:55], v[56:59], v[44:47]
	ds_read_b128 v[48:51], v39 offset:448
	ds_read_b128 v[52:55], v39 offset:416
	ds_read_b128 v[56:59], v9
	v_add_u32_e32 v9, 0x10080, v7
	s_waitcnt lgkmcnt(0)
	v_mfma_f32_16x16x32_bf16 v[2:5], v[48:51], v[56:59], v[2:5]
	v_mfma_f32_16x16x32_bf16 v[44:47], v[52:55], v[56:59], v[44:47]
	ds_read_b128 v[48:51], v39 offset:384
	ds_read_b128 v[52:55], v39 offset:352
	ds_read_b128 v[56:59], v9
	v_add_u32_e32 v9, 0x10040, v7
	s_waitcnt lgkmcnt(0)
	v_mfma_f32_16x16x32_bf16 v[2:5], v[48:51], v[56:59], v[2:5]
	v_mfma_f32_16x16x32_bf16 v[44:47], v[52:55], v[56:59], v[44:47]
	ds_read_b128 v[48:51], v39 offset:320
	ds_read_b128 v[52:55], v39 offset:288
	ds_read_b128 v[56:59], v9
	v_add_u32_e32 v9, 0x10000, v7
	s_waitcnt lgkmcnt(0)
	v_mfma_f32_16x16x32_bf16 v[2:5], v[48:51], v[56:59], v[2:5]
	v_mfma_f32_16x16x32_bf16 v[44:47], v[52:55], v[56:59], v[44:47]
	ds_read_b128 v[48:51], v39 offset:256
	ds_read_b128 v[52:55], v39 offset:224
	ds_read_b128 v[56:59], v9
	v_or_b32_e32 v9, v8, v22
	s_waitcnt lgkmcnt(0)
	v_mfma_f32_16x16x32_bf16 v[2:5], v[48:51], v[56:59], v[2:5]
	v_lshl_add_u32 v9, v9, 1, s52
	v_or_b32_e32 v8, v8, v30
	v_lshl_add_u32 v8, v8, 1, s52
	v_mfma_f32_16x16x32_bf16 v[44:47], v[52:55], v[56:59], v[44:47]
	ds_read_b128 v[48:51], v39 offset:192
	ds_read_b128 v[52:55], v39 offset:160
	ds_read_b128 v[56:59], v7 offset:65472
	s_waitcnt lgkmcnt(0)
	v_mfma_f32_16x16x32_bf16 v[2:5], v[48:51], v[56:59], v[2:5]
	v_mfma_f32_16x16x32_bf16 v[44:47], v[52:55], v[56:59], v[44:47]
	ds_read_b128 v[48:51], v39 offset:128
	ds_read_b128 v[52:55], v39 offset:96
	ds_read_b128 v[56:59], v7 offset:65408
	s_waitcnt lgkmcnt(0)
	v_mfma_f32_16x16x32_bf16 v[2:5], v[48:51], v[56:59], v[2:5]
	v_mfma_f32_16x16x32_bf16 v[44:47], v[52:55], v[56:59], v[44:47]
	ds_read_b128 v[48:51], v39 offset:32
	ds_read_b128 v[52:55], v39 offset:64
	ds_read_b128 v[56:59], v7 offset:65344
	v_ashrrev_i32_e32 v7, 31, v6
	s_waitcnt lgkmcnt(0)
	v_mfma_f32_16x16x32_bf16 v[52:55], v[52:55], v[56:59], v[2:5]
	v_mfma_f32_16x16x32_bf16 v[2:5], v[48:51], v[56:59], v[44:47]
	v_lshlrev_b32_e32 v48, 1, v22
	v_mov_b32_e32 v49, v1
	s_nop 4
	v_mov_b32_e32 v61, v54
	v_lshlrev_b64 v[44:45], 9, v[6:7]
	v_lshl_add_u64 v[44:45], s[14:15], 0, v[44:45]
	v_lshl_add_u64 v[44:45], s[18:19], 1, v[44:45]
	v_lshl_add_u64 v[44:45], v[44:45], 0, v[48:49]
	global_load_dwordx2 v[50:51], v[44:45], off
	ds_read_b64 v[46:47], v9
	global_load_dwordx2 v[44:45], v[44:45], off offset:32
	v_mov_b32_e32 v54, v53
	v_mov_b32_e32 v60, v52
	v_lshl_add_u64 v[6:7], v[6:7], 1, s[16:17]
	s_waitcnt lgkmcnt(0)
	v_lshlrev_b32_e32 v57, 16, v47
	v_lshlrev_b32_e32 v56, 16, v46
	v_and_b32_e32 v47, 0xffff0000, v47
	v_and_b32_e32 v46, 0xffff0000, v46
	v_pk_fma_f32 v[46:47], v[24:25], v[46:47], v[54:55]
	v_pk_fma_f32 v[56:57], v[24:25], v[56:57], v[60:61]
	v_lshl_add_u64 v[6:7], v[6:7], 0, v[48:49]
	s_waitcnt vmcnt(1)
	v_lshlrev_b32_e32 v59, 16, v51
	v_lshlrev_b32_e32 v58, 16, v50
	v_and_b32_e32 v51, 0xffff0000, v51
	v_and_b32_e32 v50, 0xffff0000, v50
	v_pk_mul_f32 v[46:47], v[46:47], v[50:51]
	v_pk_mul_f32 v[56:57], v[56:57], v[58:59]
	v_and_b32_sdwa v50, v47, v236 dst_sel:DWORD dst_unused:UNUSED_PAD src0_sel:WORD_1 src1_sel:DWORD
	v_and_b32_sdwa v9, v57, v236 dst_sel:DWORD dst_unused:UNUSED_PAD src0_sel:WORD_1 src1_sel:DWORD
	v_add3_u32 v47, v47, v50, s60
	v_add3_u32 v9, v57, v9, s60
	v_and_b32_e32 v47, 0xffff0000, v47
	v_or_b32_sdwa v47, v47, v9 dst_sel:DWORD dst_unused:UNUSED_PAD src0_sel:DWORD src1_sel:WORD_1
	ds_read_b64 v[8:9], v8
	v_and_b32_sdwa v51, v46, v236 dst_sel:DWORD dst_unused:UNUSED_PAD src0_sel:WORD_1 src1_sel:DWORD
	v_and_b32_sdwa v43, v56, v236 dst_sel:DWORD dst_unused:UNUSED_PAD src0_sel:WORD_1 src1_sel:DWORD
	v_add3_u32 v46, v46, v51, s60
	v_add3_u32 v43, v56, v43, s60
	v_and_b32_e32 v46, 0xffff0000, v46
	v_or_b32_sdwa v46, v46, v43 dst_sel:DWORD dst_unused:UNUSED_PAD src0_sel:DWORD src1_sel:WORD_1
	global_store_dwordx2 v[6:7], v[46:47], off sc1
	s_waitcnt lgkmcnt(0)
	v_lshlrev_b32_e32 v47, 16, v9
	v_lshlrev_b32_e32 v46, 16, v8
	v_and_b32_e32 v9, 0xffff0000, v9
	v_and_b32_e32 v8, 0xffff0000, v8
	v_mov_b32_e32 v51, v4
	v_mov_b32_e32 v4, v3
	s_waitcnt vmcnt(1)
	v_lshlrev_b32_e32 v49, 16, v45
	v_lshlrev_b32_e32 v48, 16, v44
	v_and_b32_e32 v45, 0xffff0000, v45
	v_and_b32_e32 v44, 0xffff0000, v44
	v_mov_b32_e32 v50, v2
	v_pk_fma_f32 v[2:3], v[24:25], v[8:9], v[4:5]
	v_pk_fma_f32 v[46:47], v[24:25], v[46:47], v[50:51]
	v_pk_mul_f32 v[2:3], v[2:3], v[44:45]
	v_pk_mul_f32 v[46:47], v[46:47], v[48:49]
	v_and_b32_sdwa v8, v3, v236 dst_sel:DWORD dst_unused:UNUSED_PAD src0_sel:WORD_1 src1_sel:DWORD
	v_and_b32_sdwa v9, v2, v236 dst_sel:DWORD dst_unused:UNUSED_PAD src0_sel:WORD_1 src1_sel:DWORD
	v_and_b32_sdwa v4, v47, v236 dst_sel:DWORD dst_unused:UNUSED_PAD src0_sel:WORD_1 src1_sel:DWORD
	v_and_b32_sdwa v5, v46, v236 dst_sel:DWORD dst_unused:UNUSED_PAD src0_sel:WORD_1 src1_sel:DWORD
	v_add3_u32 v3, v3, v8, s60
	v_add3_u32 v2, v2, v9, s60
	v_add3_u32 v5, v46, v5, s60
	v_add3_u32 v4, v47, v4, s60
	v_and_b32_e32 v3, 0xffff0000, v3
	v_and_b32_e32 v2, 0xffff0000, v2
	v_or_b32_sdwa v3, v3, v4 dst_sel:DWORD dst_unused:UNUSED_PAD src0_sel:DWORD src1_sel:WORD_1
	v_or_b32_sdwa v2, v2, v5 dst_sel:DWORD dst_unused:UNUSED_PAD src0_sel:DWORD src1_sel:WORD_1
	global_store_dwordx2 v[6:7], v[2:3], off offset:32 sc1
	s_cbranch_scc0 .LBB0_983

.LBB0_976:
	v_or_b32_e32 v25, s18, v23
	v_lshl_or_b32 v44, v25, 5, v28
	v_ashrrev_i32_e32 v45, 31, v44
	v_lshl_add_u64 v[46:47], s[16:17], 1, v[16:17]
	v_lshlrev_b64 v[50:51], 1, v[44:45]
	v_lshl_add_u64 v[52:53], v[46:47], 0, v[50:51]
	global_load_dwordx2 v[54:55], v[52:53], off
	v_add_u32_e32 v25, v44, v27
	v_lshl_add_u32 v25, v25, 1, 0
	v_add_u32_e32 v25, 0x10100, v25
	ds_read2_b64 v[44:47], v25 offset1:4
	v_mov_b32_e32 v61, v8
	v_mov_b32_e32 v8, v7
	v_mov_b32_e32 v60, v6
	s_lshl_b64 s[16:17], s[12:13], 14
	s_waitcnt lgkmcnt(0)
	v_lshlrev_b32_e32 v57, 16, v45
	v_lshlrev_b32_e32 v56, 16, v44
	v_and_b32_e32 v45, 0xffff0000, v45
	v_and_b32_e32 v44, 0xffff0000, v44
	v_pk_fma_f32 v[6:7], v[24:25], v[44:45], v[8:9] op_sel_hi:[0,1,1]
	v_pk_fma_f32 v[56:57], v[24:25], v[56:57], v[60:61] op_sel_hi:[0,1,1]
	s_add_u32 s16, s0, s16
	s_addc_u32 s17, s1, s17
	v_lshl_add_u64 v[48:49], s[16:17], 0, v[0:1]
	v_lshlrev_b32_e32 v45, 16, v47
	v_lshlrev_b32_e32 v44, 16, v46
	v_and_b32_e32 v47, 0xffff0000, v47
	v_and_b32_e32 v46, 0xffff0000, v46
	v_readfirstlane_b32 s22, v10
	s_waitcnt vmcnt(0)
	v_lshlrev_b32_e32 v59, 16, v55
	v_lshlrev_b32_e32 v58, 16, v54
	v_and_b32_e32 v55, 0xffff0000, v55
	v_and_b32_e32 v54, 0xffff0000, v54
	v_pk_mul_f32 v[6:7], v[6:7], v[54:55]
	v_pk_mul_f32 v[56:57], v[56:57], v[58:59]
	v_and_b32_sdwa v25, v7, v236 dst_sel:DWORD dst_unused:UNUSED_PAD src0_sel:WORD_1 src1_sel:DWORD
	v_and_b32_sdwa v43, v6, v236 dst_sel:DWORD dst_unused:UNUSED_PAD src0_sel:WORD_1 src1_sel:DWORD
	v_and_b32_sdwa v8, v57, v236 dst_sel:DWORD dst_unused:UNUSED_PAD src0_sel:WORD_1 src1_sel:DWORD
	v_and_b32_sdwa v9, v56, v236 dst_sel:DWORD dst_unused:UNUSED_PAD src0_sel:WORD_1 src1_sel:DWORD
	v_add3_u32 v7, v7, v25, s60
	v_add3_u32 v6, v6, v43, s60
	v_add3_u32 v9, v56, v9, s60
	v_add3_u32 v8, v57, v8, s60
	v_and_b32_e32 v7, 0xffff0000, v7
	v_and_b32_e32 v6, 0xffff0000, v6
	v_or_b32_sdwa v7, v7, v8 dst_sel:DWORD dst_unused:UNUSED_PAD src0_sel:DWORD src1_sel:WORD_1
	v_or_b32_sdwa v6, v6, v9 dst_sel:DWORD dst_unused:UNUSED_PAD src0_sel:DWORD src1_sel:WORD_1
	v_lshl_add_u64 v[8:9], v[48:49], 0, v[50:51]
	global_store_dwordx2 v[8:9], v[6:7], off sc1
	global_load_dwordx2 v[6:7], v[52:53], off offset:32
	v_mov_b32_e32 v51, v4
	v_mov_b32_e32 v4, v3
	v_mov_b32_e32 v50, v2
	v_pk_fma_f32 v[2:3], v[24:25], v[46:47], v[4:5] op_sel_hi:[0,1,1]
	v_pk_fma_f32 v[44:45], v[24:25], v[44:45], v[50:51] op_sel_hi:[0,1,1]
	s_waitcnt vmcnt(0)
	v_lshlrev_b32_e32 v49, 16, v7
	v_lshlrev_b32_e32 v48, 16, v6
	v_and_b32_e32 v7, 0xffff0000, v7
	v_and_b32_e32 v6, 0xffff0000, v6
	v_pk_mul_f32 v[2:3], v[2:3], v[6:7]
	v_pk_mul_f32 v[44:45], v[44:45], v[48:49]
	v_and_b32_sdwa v6, v3, v236 dst_sel:DWORD dst_unused:UNUSED_PAD src0_sel:WORD_1 src1_sel:DWORD
	v_and_b32_sdwa v7, v2, v236 dst_sel:DWORD dst_unused:UNUSED_PAD src0_sel:WORD_1 src1_sel:DWORD
	v_and_b32_sdwa v4, v45, v236 dst_sel:DWORD dst_unused:UNUSED_PAD src0_sel:WORD_1 src1_sel:DWORD
	v_and_b32_sdwa v5, v44, v236 dst_sel:DWORD dst_unused:UNUSED_PAD src0_sel:WORD_1 src1_sel:DWORD
	v_add3_u32 v3, v3, v6, s60
	v_add3_u32 v2, v2, v7, s60
	v_add3_u32 v5, v44, v5, s60
	v_add3_u32 v4, v45, v4, s60
	v_and_b32_e32 v3, 0xffff0000, v3
	v_and_b32_e32 v2, 0xffff0000, v2
	v_or_b32_sdwa v3, v3, v4 dst_sel:DWORD dst_unused:UNUSED_PAD src0_sel:DWORD src1_sel:WORD_1
	v_or_b32_sdwa v2, v2, v5 dst_sel:DWORD dst_unused:UNUSED_PAD src0_sel:DWORD src1_sel:WORD_1
	global_store_dwordx2 v[8:9], v[2:3], off offset:32 sc1
	v_mov_b32_e32 v2, 0
	v_mov_b32_e32 v3, 0
	v_mov_b32_e32 v4, 0
	v_mov_b32_e32 v5, 0
	s_barrier
	s_and_saveexec_b64 s[18:19], s[10:11]
	s_cbranch_execz .LBB0_978
	s_lshl_b64 s[20:21], s[12:13], 10
	v_lshl_add_u64 v[2:3], v[18:19], 0, s[20:21]
	global_load_dwordx4 v[2:5], v[2:3], off

.LBB0_983:
	s_load_dwordx2 s[22:23], s[66:67], 0x100
	s_waitcnt vmcnt(0)
	s_barrier
	v_readlane_b32 s2, v255, 0
	s_cmp_lg_u32 s86, 0
	s_cbranch_scc1 .Lytf_nosig
	s_lshr_b32 s2, s2, 6
	s_lshl_b32 s2, s2, 7
	s_add_u32 s2, s2, 0xe803800
	s_waitcnt lgkmcnt(0)
	s_add_u32 s6, s22, s2
	s_addc_u32 s7, s23, 0
	s_mov_b64 s[2:3], exec
	s_mov_b64 exec, 1
	v_mov_b32_e32 v0, 1
	global_atomic_add v1, v0, s[6:7]
	s_mov_b64 exec, s[2:3]

.LBB0_1201:
	s_waitcnt vmcnt(0)
	s_waitcnt lgkmcnt(0)
	s_barrier
	s_and_saveexec_b64 s[6:7], s[10:11]
	s_branch .LBB0_1253
	v_readlane_b32 s1, v254, 51
	s_waitcnt vmcnt(0) expcnt(0) lgkmcnt(0)
	s_and_b32 s0, s0, 15
	v_mov_b32_e32 v0, s1
	ds_read_b32 v3, v0
	v_readlane_b32 s1, v254, 52
	s_waitcnt lgkmcnt(0)
	v_cmp_ne_u32_e32 vcc, 0, v3
	v_mov_b32_e32 v0, s1
	ds_read_b32 v2, v0
	s_cbranch_vccnz .LBB0_1217
	s_add_u32 s10, s8, 0xe800200
	s_addc_u32 s11, s9, 0
	s_add_u32 s12, s8, 0xe800400
	s_addc_u32 s13, s9, 0
	s_add_u32 s14, s8, 0xe800500
	s_addc_u32 s15, s9, 0
	s_add_u32 s16, s8, 0xe800600
	s_addc_u32 s17, s9, 0
	s_add_u32 s18, s8, 0xe800700
	s_addc_u32 s19, s9, 0
	s_add_u32 s20, s8, 0xe800800
	s_addc_u32 s21, s9, 0
	s_add_u32 s22, s8, 0xe800900
	s_addc_u32 s23, s9, 0
	s_add_u32 s24, s8, 0xe800a00
	s_addc_u32 s25, s9, 0
	s_add_u32 s26, s8, 0xe800b00
	s_addc_u32 s27, s9, 0
	s_add_u32 s28, s8, 0xe800c00
	s_addc_u32 s29, s9, 0
	s_add_u32 s30, s8, 0xe800d00
	s_addc_u32 s31, s9, 0
	s_add_u32 s34, s8, 0xe800e00
	s_addc_u32 s35, s9, 0
	s_add_u32 s36, s8, 0xe800f00
	s_addc_u32 s37, s9, 0
	s_add_u32 s38, s8, 0xe801000
	s_addc_u32 s39, s9, 0
	s_add_u32 s40, s8, 0xe801100
	s_addc_u32 s41, s9, 0
	s_add_u32 s42, s8, 0xe801200
	s_addc_u32 s43, s9, 0
	s_add_u32 s46, s8, 0xe801300
	s_addc_u32 s47, s9, 0
	s_mov_b32 s1, 1
	s_branch .LBB0_1205

.LBB0_1253:
	s_or_b64 exec, exec, s[6:7]
	s_mov_b64 s[6:7], s[66:67]
	v_mov_b32_e32 v0, v1
	s_waitcnt lgkmcnt(0)
	s_barrier
	s_nop 0
	v_mbcnt_lo_u32_b32 v0, -1, v0
	v_mbcnt_hi_u32_b32 v0, -1, v0
	v_add_u32_e32 v2, s86, v0
	s_nop 0
	v_readfirstlane_b32 s0, v2
	s_ashr_i32 s2, s0, 6
	s_add_i32 s0, s2, s55
	s_cmpk_gt_i32 s0, 0x1ff
	s_cbranch_scc1 .LBB0_1256
	s_load_dwordx2 s[6:7], s[6:7], 0x100
	v_and_b32_e32 v4, 7, v0
	v_bfe_u32 v12, v0, 3, 3
	v_lshlrev_b32_e32 v0, 4, v4
	s_lshl_b32 s1, s2, 14
	s_waitcnt lgkmcnt(0)
	v_lshl_add_u64 v[2:3], s[6:7], 0, v[0:1]
	s_and_b32 s3, s2, 3
	s_lshl_b32 s3, s3, 7
	s_add_u32 s3, s3, 0xe803800
	s_add_u32 s6, s6, s3
	s_addc_u32 s7, s7, 0
	v_readlane_b32 s3, v255, 21
	s_nop 3
	s_add_i32 s3, s3, 1
	s_lshl_b32 s3, s3, 6
.Lytf_poll:
	global_load_dword v5, v1, s[6:7] sc1
	s_waitcnt vmcnt(0)
	v_cmp_le_u32_e32 vcc, s3, v5
	s_cbranch_vccnz .Lytf_go
	s_sleep 2
	s_branch .Lytf_poll
.Lytf_go:
	s_mov_b64 s[6:7], 0xb800000
	v_lshl_add_u64 v[6:7], v[2:3], 0, s[6:7]
	s_mov_b64 s[6:7], 0xd800000
	s_add_i32 s1, s1, 0
	v_mul_u32_u24_e32 v4, 0x420, v4
	v_lshl_add_u64 v[8:9], v[2:3], 0, s[6:7]
	v_lshlrev_b32_e32 v2, 1, v12
	v_add_u32_e32 v0, s1, v0
	v_add3_u32 v13, s1, v4, v2
	s_lshl_b32 s1, s2, 4
	v_readlane_b32 s3, v254, 48
	v_mul_u32_u24_e32 v2, 0x84, v12
	s_add_i32 s1, s3, s1
	s_lshl_b32 s2, s2, 6
	v_readlane_b32 s3, v254, 7
	v_or_b32_e32 v14, 8, v12
	v_or_b32_e32 v15, 16, v12
	v_or_b32_e32 v16, 24, v12
	v_or_b32_e32 v17, 32, v12
	v_or_b32_e32 v18, 40, v12
	v_or_b32_e32 v19, 48, v12
	v_or_b32_e32 v20, 56, v12
	s_add_i32 s2, s3, s2
	v_add_u32_e32 v21, v0, v2
.LBB0_1255:
	s_and_b32 s3, s2, 0xc0
	s_and_b32 s6, s1, 0xffffffc0
	v_or_b32_e32 v0, s3, v12
	s_ashr_i32 s7, s6, 31
	v_lshl_add_u64 v[2:3], s[6:7], 1, v[6:7]
	v_lshlrev_b32_e32 v0, 14, v0
	v_lshl_add_u64 v[10:11], v[2:3], 0, v[0:1]
	v_add_co_u32_e32 v22, vcc, 0x20000, v10
	global_load_dwordx4 v[2:5], v[10:11], off sc1
	s_nop 0
	v_addc_co_u32_e32 v23, vcc, 0, v11, vcc
	global_load_dwordx4 v[22:25], v[22:23], off sc1
	v_add_co_u32_e32 v26, vcc, 0x40000, v10
	v_add_u32_e32 v0, 0x420, v21
	s_nop 0
	v_addc_co_u32_e32 v27, vcc, 0, v11, vcc
	global_load_dwordx4 v[26:29], v[26:27], off sc1
	v_add_co_u32_e32 v30, vcc, 0x60000, v10
	s_lshl_b32 s44, s3, 1
	s_nop 0
	v_addc_co_u32_e32 v31, vcc, 0, v11, vcc
	global_load_dwordx4 v[30:33], v[30:31], off sc1
	v_add_co_u32_e32 v34, vcc, 0x80000, v10
	s_add_i32 s0, s0, s68
	s_nop 0
	v_addc_co_u32_e32 v35, vcc, 0, v11, vcc
	global_load_dwordx4 v[34:37], v[34:35], off sc1
	v_add_co_u32_e32 v38, vcc, 0xa0000, v10
	s_add_i32 s2, s2, s58
	s_nop 0
	v_addc_co_u32_e32 v39, vcc, 0, v11, vcc
	global_load_dwordx4 v[38:41], v[38:39], off sc1
	v_add_co_u32_e32 v42, vcc, 0xc0000, v10
	s_nop 1
	v_addc_co_u32_e32 v43, vcc, 0, v11, vcc
	global_load_dwordx4 v[42:45], v[42:43], off sc1
	v_add_co_u32_e32 v10, vcc, 0xe0000, v10
	s_nop 1
	v_addc_co_u32_e32 v11, vcc, 0, v11, vcc
	global_load_dwordx4 v[46:49], v[10:11], off sc1
	v_lshl_add_u64 v[10:11], v[8:9], 0, s[44:45]
	s_waitcnt vmcnt(7)
	ds_write2_b32 v21, v2, v3 offset1:1
	ds_write2_b32 v21, v4, v5 offset0:2 offset1:3
	s_waitcnt vmcnt(6)
	ds_write2_b32 v0, v22, v23 offset1:1
	v_add_u32_e32 v0, 0x428, v21
	ds_write2_b32 v0, v24, v25 offset1:1
	v_add_u32_e32 v0, 0x840, v21
	v_or_b32_e32 v22, s6, v12
	v_ashrrev_i32_e32 v23, 31, v22
	s_waitcnt vmcnt(5)
	ds_write2_b32 v0, v26, v27 offset1:1
	v_add_u32_e32 v0, 0x848, v21
	ds_write2_b32 v0, v28, v29 offset1:1
	v_add_u32_e32 v0, 0xc60, v21
	v_lshlrev_b64 v[22:23], 11, v[22:23]
	v_lshl_add_u64 v[22:23], v[10:11], 0, v[22:23]
	s_waitcnt vmcnt(4)
	ds_write2_b32 v0, v30, v31 offset1:1
	v_add_u32_e32 v0, 0xc68, v21
	ds_write2_b32 v0, v32, v33 offset1:1
	v_add_u32_e32 v0, 0x1080, v21
	s_waitcnt vmcnt(3)
	ds_write2_b32 v0, v34, v35 offset1:1
	v_add_u32_e32 v0, 0x1088, v21
	ds_write2_b32 v0, v36, v37 offset1:1
	v_add_u32_e32 v0, 0x14a0, v21
	s_waitcnt vmcnt(2)
	ds_write2_b32 v0, v38, v39 offset1:1
	v_add_u32_e32 v0, 0x14a8, v21
	ds_write2_b32 v0, v40, v41 offset1:1
	v_add_u32_e32 v0, 0x18c0, v21
	s_waitcnt vmcnt(1)
	ds_write2_b32 v0, v42, v43 offset1:1
	v_add_u32_e32 v0, 0x18c8, v21
	ds_write2_b32 v0, v44, v45 offset1:1
	v_add_u32_e32 v0, 0x1ce0, v21
	s_waitcnt vmcnt(0)
	ds_write2_b32 v0, v46, v47 offset1:1
	v_add_u32_e32 v0, 0x1ce8, v21
	ds_write2_b32 v0, v48, v49 offset1:1
	s_waitcnt lgkmcnt(0)
	ds_read_u16 v0, v13 offset:132
	ds_read_u16 v2, v13
	ds_read_u16 v24, v13 offset:16
	s_waitcnt lgkmcnt(1)
	v_lshl_or_b32 v2, v0, 16, v2
	ds_read_u16 v0, v13 offset:264
	ds_read_u16 v3, v13 offset:396
	s_waitcnt lgkmcnt(0)
	v_lshl_or_b32 v3, v3, 16, v0
	ds_read_u16 v0, v13 offset:528
	ds_read_u16 v4, v13 offset:660
	s_waitcnt lgkmcnt(0)
	v_lshl_or_b32 v4, v4, 16, v0
	ds_read_u16 v0, v13 offset:792
	ds_read_u16 v5, v13 offset:924
	s_waitcnt lgkmcnt(0)
	v_lshl_or_b32 v5, v5, 16, v0
	ds_read_u16 v0, v13 offset:148
	global_store_dwordx4 v[22:23], v[2:5], off
	v_or_b32_e32 v22, s6, v14
	v_ashrrev_i32_e32 v23, 31, v22
	v_lshlrev_b64 v[22:23], 11, v[22:23]
	s_waitcnt lgkmcnt(0)
	v_lshl_or_b32 v2, v0, 16, v24
	ds_read_u16 v0, v13 offset:280
	ds_read_u16 v3, v13 offset:412
	v_lshl_add_u64 v[22:23], v[10:11], 0, v[22:23]
	s_waitcnt lgkmcnt(0)
	v_lshl_or_b32 v3, v3, 16, v0
	ds_read_u16 v0, v13 offset:544
	ds_read_u16 v4, v13 offset:676
	s_waitcnt lgkmcnt(0)
	v_lshl_or_b32 v4, v4, 16, v0
	ds_read_u16 v0, v13 offset:808
	ds_read_u16 v5, v13 offset:940
	s_waitcnt lgkmcnt(0)
	v_lshl_or_b32 v5, v5, 16, v0
	global_store_dwordx4 v[22:23], v[2:5], off
	ds_read_u16 v0, v13 offset:164
	ds_read_u16 v2, v13 offset:32
	ds_read_u16 v24, v13 offset:48
	v_or_b32_e32 v22, s6, v15
	v_ashrrev_i32_e32 v23, 31, v22
	v_lshlrev_b64 v[22:23], 11, v[22:23]
	s_waitcnt lgkmcnt(1)
	v_lshl_or_b32 v2, v0, 16, v2
	ds_read_u16 v0, v13 offset:296
	ds_read_u16 v3, v13 offset:428
	v_lshl_add_u64 v[22:23], v[10:11], 0, v[22:23]
	s_waitcnt lgkmcnt(0)
	v_lshl_or_b32 v3, v3, 16, v0
	ds_read_u16 v0, v13 offset:560
	ds_read_u16 v4, v13 offset:692
	s_waitcnt lgkmcnt(0)
	v_lshl_or_b32 v4, v4, 16, v0
	ds_read_u16 v0, v13 offset:824
	ds_read_u16 v5, v13 offset:956
	s_waitcnt lgkmcnt(0)
	v_lshl_or_b32 v5, v5, 16, v0
	ds_read_u16 v0, v13 offset:180
	global_store_dwordx4 v[22:23], v[2:5], off
	v_or_b32_e32 v22, s6, v16
	v_ashrrev_i32_e32 v23, 31, v22
	v_lshlrev_b64 v[22:23], 11, v[22:23]
	s_waitcnt lgkmcnt(0)
	v_lshl_or_b32 v2, v0, 16, v24
	ds_read_u16 v0, v13 offset:312
	ds_read_u16 v3, v13 offset:444
	v_lshl_add_u64 v[22:23], v[10:11], 0, v[22:23]
	s_waitcnt lgkmcnt(0)
	v_lshl_or_b32 v3, v3, 16, v0
	ds_read_u16 v0, v13 offset:576
	ds_read_u16 v4, v13 offset:708
	s_waitcnt lgkmcnt(0)
	v_lshl_or_b32 v4, v4, 16, v0
	ds_read_u16 v0, v13 offset:840
	ds_read_u16 v5, v13 offset:972
	s_waitcnt lgkmcnt(0)
	v_lshl_or_b32 v5, v5, 16, v0
	global_store_dwordx4 v[22:23], v[2:5], off
	ds_read_u16 v0, v13 offset:64
	ds_read_u16 v2, v13 offset:196
	v_or_b32_e32 v22, s6, v17
	v_ashrrev_i32_e32 v23, 31, v22
	v_lshlrev_b64 v[22:23], 11, v[22:23]
	v_lshl_add_u64 v[22:23], v[10:11], 0, v[22:23]
	s_waitcnt lgkmcnt(0)
	v_lshl_or_b32 v2, v2, 16, v0
	ds_read_u16 v0, v13 offset:328
	ds_read_u16 v3, v13 offset:460
	s_waitcnt lgkmcnt(0)
	v_lshl_or_b32 v3, v3, 16, v0
	ds_read_u16 v0, v13 offset:592
	ds_read_u16 v4, v13 offset:724
	s_waitcnt lgkmcnt(0)
	v_lshl_or_b32 v4, v4, 16, v0
	ds_read_u16 v0, v13 offset:856
	ds_read_u16 v5, v13 offset:988
	s_waitcnt lgkmcnt(0)
	v_lshl_or_b32 v5, v5, 16, v0
	global_store_dwordx4 v[22:23], v[2:5], off
	ds_read_u16 v0, v13 offset:80
	ds_read_u16 v2, v13 offset:212
	v_or_b32_e32 v22, s6, v18
	v_ashrrev_i32_e32 v23, 31, v22
	v_lshlrev_b64 v[22:23], 11, v[22:23]
	v_lshl_add_u64 v[22:23], v[10:11], 0, v[22:23]
	s_waitcnt lgkmcnt(0)
	v_lshl_or_b32 v2, v2, 16, v0
	ds_read_u16 v0, v13 offset:344
	ds_read_u16 v3, v13 offset:476
	s_waitcnt lgkmcnt(0)
	v_lshl_or_b32 v3, v3, 16, v0
	ds_read_u16 v0, v13 offset:608
	ds_read_u16 v4, v13 offset:740
	s_waitcnt lgkmcnt(0)
	v_lshl_or_b32 v4, v4, 16, v0
	ds_read_u16 v0, v13 offset:872
	ds_read_u16 v5, v13 offset:1004
	s_waitcnt lgkmcnt(0)
	v_lshl_or_b32 v5, v5, 16, v0
	global_store_dwordx4 v[22:23], v[2:5], off
	ds_read_u16 v0, v13 offset:96
	ds_read_u16 v2, v13 offset:228
	v_or_b32_e32 v22, s1, v19
	v_ashrrev_i32_e32 v23, 31, v22
	v_lshlrev_b64 v[22:23], 11, v[22:23]
	v_lshl_add_u64 v[22:23], v[10:11], 0, v[22:23]
	s_waitcnt lgkmcnt(0)
	v_lshl_or_b32 v2, v2, 16, v0
	ds_read_u16 v0, v13 offset:360
	ds_read_u16 v3, v13 offset:492
	s_waitcnt lgkmcnt(0)
	v_lshl_or_b32 v3, v3, 16, v0
	ds_read_u16 v0, v13 offset:624
	ds_read_u16 v4, v13 offset:756
	s_waitcnt lgkmcnt(0)
	v_lshl_or_b32 v4, v4, 16, v0
	ds_read_u16 v0, v13 offset:888
	ds_read_u16 v5, v13 offset:1020
	s_waitcnt lgkmcnt(0)
	v_lshl_or_b32 v5, v5, 16, v0
	global_store_dwordx4 v[22:23], v[2:5], off
	ds_read_u16 v0, v13 offset:112
	ds_read_u16 v2, v13 offset:244
	v_or_b32_e32 v22, s1, v20
	v_ashrrev_i32_e32 v23, 31, v22
	v_lshlrev_b64 v[22:23], 11, v[22:23]
	v_lshl_add_u64 v[10:11], v[10:11], 0, v[22:23]
	s_waitcnt lgkmcnt(0)
	v_lshl_or_b32 v2, v2, 16, v0
	ds_read_u16 v0, v13 offset:376
	ds_read_u16 v3, v13 offset:508
	s_add_i32 s1, s1, s50
	s_cmpk_lt_i32 s0, 0x200
	s_waitcnt lgkmcnt(0)
	v_lshl_or_b32 v3, v3, 16, v0
	ds_read_u16 v0, v13 offset:640
	ds_read_u16 v4, v13 offset:772
	s_waitcnt lgkmcnt(0)
	v_lshl_or_b32 v4, v4, 16, v0
	ds_read_u16 v0, v13 offset:904
	ds_read_u16 v5, v13 offset:1036
	s_waitcnt lgkmcnt(0)
	v_lshl_or_b32 v5, v5, 16, v0
	global_store_dwordx4 v[10:11], v[2:5], off
	s_waitcnt lgkmcnt(0)
	s_cbranch_scc1 .LBB0_1255
